# seams: L1 invalidate issued at arrival (overlaps the arrival atomic); P8 kv-up tiles split 2/4 instead of 3/3 to balance against the q-up pass
# speedup vs baseline: 1.0609x; 1.0014x over previous
; DI unsigned xb_add(unsigned* p, unsigned v) { return __hip_atomic_fetch_add(p, v, __ATOMIC_RELAXED, __HIP_MEMORY_SCOPE_AGENT); }
; DI void xcd_barrier(const XcdBarrier& b) {
;     ...
;   if (threadIdx.x == 0) {
;     unsigned* bar = b.bar;
;     __builtin_amdgcn_s_waitcnt(0);
;     unsigned nloc = b.st[0], nx = b.st[1];
;     if (nloc == 0u) { xcd_barrier_complete(bar, b.x, nloc, nx); b.st[0] = nloc; b.st[1] = nx; }
;     const unsigned old = xb_add(&bar[XB_XSUB(b.x)], 1u);
.LBB0_393:
	s_mov_b64 s[6:7], exec
	v_readlane_b32 s4, v254, 5
	s_lshl_b32 s4, s4, 8
	v_mbcnt_lo_u32_b32 v1, s6, 0
	s_add_u32 s4, s92, s4
	v_mbcnt_hi_u32_b32 v1, s7, v1
	s_addc_u32 s5, s93, 0
	v_cmp_eq_u32_e32 vcc, 0, v1
	s_and_saveexec_b64 s[8:9], vcc
	s_cbranch_execz .LBB0_395
	v_mov_b32_e32 v255, 0
	ds_read_b32 v255, v255 offset:264
	s_waitcnt lgkmcnt(0)
	v_readfirstlane_b32 s100, v255
	s_cmp_lg_u32 s100, 0
	s_cbranch_scc0 .Lei_a_2
	buffer_inv sc1
.Lei_a_2:
	s_bcnt1_i32_b64 s6, s[6:7]
	v_mov_b32_e32 v4, 0x1000
	v_mov_b32_e32 v5, s6
	global_atomic_add v4, v4, v5, s[4:5] offset:1024 sc0

; DI unsigned xb_ld(unsigned* p) { return __hip_atomic_load(p, __ATOMIC_RELAXED, __HIP_MEMORY_SCOPE_AGENT); }
; DI unsigned xb_add(unsigned* p, unsigned v) { return __hip_atomic_fetch_add(p, v, __ATOMIC_RELAXED, __HIP_MEMORY_SCOPE_AGENT); }
; #define XB_SPIN(cond, bar) do { unsigned _sp = 0; while (cond) { __builtin_amdgcn_s_sleep(1); \
;     if ((++_sp & 255u) == 0u) { if (xb_ld(&(bar)[XB_TMO])) break; if (_sp > XB_SPIN_CAP) { atomicAdd(&(bar)[XB_TMO], 1u); break; } } } } while (0)
; DI void xcd_barrier(const XcdBarrier& b) {
;     ...
;     if (old + 1u == (gen + 1u) * nloc) {
;       __builtin_amdgcn_fence(__ATOMIC_RELEASE, "agent");
;       asm volatile("s_waitcnt vmcnt(0)" ::: "memory");
;       const unsigned og = xb_add(&bar[XB_TOP], 1u);
;       const unsigned tg = og / nx;
;       if (og + 1u == (tg + 1u) * nx) xb_add(&bar[XB_TOPGEN], 1u);
;       else XB_SPIN(xb_ld(&bar[XB_TOPGEN]) == tg, bar);
;       __builtin_amdgcn_fence(__ATOMIC_ACQUIRE, "agent");
;       xb_add(&bar[XB_XGEN(b.x)], 1u);
;       asm volatile("s_waitcnt vmcnt(0)" ::: "memory");
;     } else {
;       XB_SPIN(xb_ld(&bar[XB_XGEN(b.x)]) == gen, bar);
;       __builtin_amdgcn_fence(__ATOMIC_ACQUIRE, "agent");
;       asm volatile("s_waitcnt vmcnt(0)" ::: "memory");
;     }
.LBB0_408:
	s_or_b64 exec, exec, s[8:9]
	s_waitcnt vmcnt(0)
	s_cmp_lg_u32 s100, 0
	s_cbranch_scc1 .Lei_b_2
	buffer_inv sc1
.Lei_b_2:
	s_waitcnt vmcnt(0)
.LBB0_409:
	s_andn2_saveexec_b64 s[6:7], s[6:7]
	s_cbranch_execz .LBB0_429
	s_mov_b64 s[6:7], exec
	v_mov_b32_e32 v255, 0
	ds_read_b32 v255, v255 offset:264
	s_waitcnt lgkmcnt(0)
	v_cmp_ne_u32_e32 vcc, 0, v255
	s_cbranch_vccnz .LBB0_426
	buffer_wbl2 sc1
	s_waitcnt lgkmcnt(0)
	s_waitcnt vmcnt(0)
	v_mbcnt_lo_u32_b32 v1, s6, 0
	v_mbcnt_hi_u32_b32 v1, s7, v1
	v_cmp_eq_u32_e32 vcc, 0, v1
	s_and_saveexec_b64 s[8:9], vcc
	s_cbranch_execz .LBB0_412
	s_bcnt1_i32_b64 s6, s[6:7]
	v_mov_b32_e32 v3, 0xbfa3000
	v_mov_b32_e32 v4, s6
	global_atomic_add v3, v3, v4, s[86:87] offset:1024 sc0

; DI unsigned xb_add(unsigned* p, unsigned v) { return __hip_atomic_fetch_add(p, v, __ATOMIC_RELAXED, __HIP_MEMORY_SCOPE_AGENT); }
; DI void xcd_barrier(const XcdBarrier& b) {
;     ...
;       __builtin_amdgcn_fence(__ATOMIC_ACQUIRE, "agent");
;       xb_add(&bar[XB_XGEN(b.x)], 1u);
;       asm volatile("s_waitcnt vmcnt(0)" ::: "memory");
.LBB0_426:
	s_or_b64 exec, exec, s[6:7]
	s_mov_b64 s[6:7], exec
	v_mbcnt_lo_u32_b32 v1, s6, 0
	v_mbcnt_hi_u32_b32 v1, s7, v1
	v_cmp_eq_u32_e32 vcc, 0, v1
	s_waitcnt vmcnt(0)
	s_cmp_lg_u32 s100, 0
	s_cbranch_scc1 .Lei_c_2
	buffer_inv sc1
.Lei_c_2:
	s_and_saveexec_b64 s[8:9], vcc
	s_cbranch_execz .LBB0_428
	s_bcnt1_i32_b64 s6, s[6:7]
	v_mov_b32_e32 v1, 0x2000
	v_mov_b32_e32 v2, s6
	global_atomic_add v1, v2, s[4:5] offset:1024

; DI unsigned xb_add(unsigned* p, unsigned v) { return __hip_atomic_fetch_add(p, v, __ATOMIC_RELAXED, __HIP_MEMORY_SCOPE_AGENT); }
; DI void xcd_barrier(const XcdBarrier& b) {
;     ...
;   if (threadIdx.x == 0) {
;     unsigned* bar = b.bar;
;     __builtin_amdgcn_s_waitcnt(0);
;     unsigned nloc = b.st[0], nx = b.st[1];
;     if (nloc == 0u) { xcd_barrier_complete(bar, b.x, nloc, nx); b.st[0] = nloc; b.st[1] = nx; }
;     const unsigned old = xb_add(&bar[XB_XSUB(b.x)], 1u);
.LBB0_516:
	s_mov_b64 s[6:7], exec
	v_readlane_b32 s2, v254, 5
	s_lshl_b32 s2, s2, 8
	v_mbcnt_lo_u32_b32 v0, s6, 0
	s_add_u32 s4, s92, s2
	v_mbcnt_hi_u32_b32 v0, s7, v0
	s_addc_u32 s5, s93, 0
	v_cmp_eq_u32_e32 vcc, 0, v0
	s_and_saveexec_b64 s[8:9], vcc
	s_cbranch_execz .LBB0_518
	v_mov_b32_e32 v255, 0
	ds_read_b32 v255, v255 offset:264
	s_waitcnt lgkmcnt(0)
	v_readfirstlane_b32 s100, v255
	s_cmp_lg_u32 s100, 0
	s_cbranch_scc0 .Lei_a_3
	buffer_inv sc1
.Lei_a_3:
	s_bcnt1_i32_b64 s2, s[6:7]
	v_mov_b32_e32 v3, 0x1000
	v_mov_b32_e32 v4, s2
	global_atomic_add v3, v3, v4, s[4:5] offset:1024 sc0

; DI unsigned xb_ld(unsigned* p) { return __hip_atomic_load(p, __ATOMIC_RELAXED, __HIP_MEMORY_SCOPE_AGENT); }
; DI unsigned xb_add(unsigned* p, unsigned v) { return __hip_atomic_fetch_add(p, v, __ATOMIC_RELAXED, __HIP_MEMORY_SCOPE_AGENT); }
; #define XB_SPIN(cond, bar) do { unsigned _sp = 0; while (cond) { __builtin_amdgcn_s_sleep(1); \
;     if ((++_sp & 255u) == 0u) { if (xb_ld(&(bar)[XB_TMO])) break; if (_sp > XB_SPIN_CAP) { atomicAdd(&(bar)[XB_TMO], 1u); break; } } } } while (0)
; DI void xcd_barrier(const XcdBarrier& b) {
;     ...
;     if (old + 1u == (gen + 1u) * nloc) {
;       __builtin_amdgcn_fence(__ATOMIC_RELEASE, "agent");
;       asm volatile("s_waitcnt vmcnt(0)" ::: "memory");
;       const unsigned og = xb_add(&bar[XB_TOP], 1u);
;       const unsigned tg = og / nx;
;       if (og + 1u == (tg + 1u) * nx) xb_add(&bar[XB_TOPGEN], 1u);
;       else XB_SPIN(xb_ld(&bar[XB_TOPGEN]) == tg, bar);
.Lei_b_3:
	s_waitcnt vmcnt(0)
.LBB0_532:
	s_andn2_saveexec_b64 s[2:3], s[6:7]
	s_cbranch_execz .LBB0_552
	s_mov_b64 s[6:7], exec
	v_mov_b32_e32 v255, 0
	ds_read_b32 v255, v255 offset:264
	s_waitcnt lgkmcnt(0)
	v_cmp_ne_u32_e32 vcc, 0, v255
	s_cbranch_vccz .Lxl_full_3
	v_mov_b32_e32 v255, 0xbfa0208
	v_mov_b32_e32 v0, 1
	global_atomic_add v255, v0, s[86:87]
	s_branch .LBB0_549

; DI unsigned xb_add(unsigned* p, unsigned v) { return __hip_atomic_fetch_add(p, v, __ATOMIC_RELAXED, __HIP_MEMORY_SCOPE_AGENT); }
; DI void xcd_barrier(const XcdBarrier& b) {
;     ...
;       __builtin_amdgcn_fence(__ATOMIC_ACQUIRE, "agent");
;       xb_add(&bar[XB_XGEN(b.x)], 1u);
;       asm volatile("s_waitcnt vmcnt(0)" ::: "memory");
.LBB0_549:
	s_or_b64 exec, exec, s[6:7]
	s_mov_b64 s[6:7], exec
	v_mbcnt_lo_u32_b32 v0, s6, 0
	v_mbcnt_hi_u32_b32 v0, s7, v0
	v_cmp_eq_u32_e32 vcc, 0, v0
	s_waitcnt vmcnt(0)
	s_cmp_lg_u32 s100, 0
	s_cbranch_scc1 .Lei_c_3
	buffer_inv sc1
.Lei_c_3:
	s_and_saveexec_b64 s[8:9], vcc
	s_cbranch_execz .LBB0_551
	s_bcnt1_i32_b64 s2, s[6:7]
	v_mov_b32_e32 v0, 0x2000
	v_mov_b32_e32 v1, s2
	global_atomic_add v0, v1, s[4:5] offset:1024

; DI unsigned xb_add(unsigned* p, unsigned v) { return __hip_atomic_fetch_add(p, v, __ATOMIC_RELAXED, __HIP_MEMORY_SCOPE_AGENT); }
; DI void xcd_barrier(const XcdBarrier& b) {
;     ...
;   if (threadIdx.x == 0) {
;     unsigned* bar = b.bar;
;     __builtin_amdgcn_s_waitcnt(0);
;     unsigned nloc = b.st[0], nx = b.st[1];
;     if (nloc == 0u) { xcd_barrier_complete(bar, b.x, nloc, nx); b.st[0] = nloc; b.st[1] = nx; }
;     const unsigned old = xb_add(&bar[XB_XSUB(b.x)], 1u);
.LBB0_602:
	s_mov_b64 s[8:9], exec
	s_lshl_b32 s2, s78, 8
	v_mbcnt_lo_u32_b32 v0, s8, 0
	s_add_u32 s6, s92, s2
	v_mbcnt_hi_u32_b32 v0, s9, v0
	s_addc_u32 s7, s93, 0
	v_cmp_eq_u32_e32 vcc, 0, v0
	s_and_saveexec_b64 s[10:11], vcc
	s_cbranch_execz .LBB0_604
	v_mov_b32_e32 v255, 0
	ds_read_b32 v255, v255 offset:264
	s_waitcnt lgkmcnt(0)
	v_readfirstlane_b32 s100, v255
	s_cmp_lg_u32 s100, 0
	s_cbranch_scc0 .Lei_a_4
	buffer_inv sc1
.Lei_a_4:
	s_bcnt1_i32_b64 s2, s[8:9]
	v_mov_b32_e32 v3, 0x1000
	v_mov_b32_e32 v4, s2
	global_atomic_add v3, v3, v4, s[6:7] offset:1024 sc0

; DI unsigned xb_ld(unsigned* p) { return __hip_atomic_load(p, __ATOMIC_RELAXED, __HIP_MEMORY_SCOPE_AGENT); }
; DI unsigned xb_add(unsigned* p, unsigned v) { return __hip_atomic_fetch_add(p, v, __ATOMIC_RELAXED, __HIP_MEMORY_SCOPE_AGENT); }
; #define XB_SPIN(cond, bar) do { unsigned _sp = 0; while (cond) { __builtin_amdgcn_s_sleep(1); \
;     if ((++_sp & 255u) == 0u) { if (xb_ld(&(bar)[XB_TMO])) break; if (_sp > XB_SPIN_CAP) { atomicAdd(&(bar)[XB_TMO], 1u); break; } } } } while (0)
; DI void xcd_barrier(const XcdBarrier& b) {
;     ...
;     if (old + 1u == (gen + 1u) * nloc) {
;       __builtin_amdgcn_fence(__ATOMIC_RELEASE, "agent");
;       asm volatile("s_waitcnt vmcnt(0)" ::: "memory");
;       const unsigned og = xb_add(&bar[XB_TOP], 1u);
;       const unsigned tg = og / nx;
;       if (og + 1u == (tg + 1u) * nx) xb_add(&bar[XB_TOPGEN], 1u);
;       else XB_SPIN(xb_ld(&bar[XB_TOPGEN]) == tg, bar);
;       __builtin_amdgcn_fence(__ATOMIC_ACQUIRE, "agent");
;       xb_add(&bar[XB_XGEN(b.x)], 1u);
;       asm volatile("s_waitcnt vmcnt(0)" ::: "memory");
;     } else {
;       XB_SPIN(xb_ld(&bar[XB_XGEN(b.x)]) == gen, bar);
;       __builtin_amdgcn_fence(__ATOMIC_ACQUIRE, "agent");
;       asm volatile("s_waitcnt vmcnt(0)" ::: "memory");
;     }
.LBB0_617:
	s_or_b64 exec, exec, s[10:11]
	s_waitcnt vmcnt(0)
	s_cmp_lg_u32 s100, 0
	s_cbranch_scc1 .Lei_b_4
	buffer_inv sc1
.Lei_b_4:
	s_waitcnt vmcnt(0)
.LBB0_618:
	s_andn2_saveexec_b64 s[2:3], s[8:9]
	s_cbranch_execz .LBB0_638
	s_mov_b64 s[8:9], exec
	v_mov_b32_e32 v255, 0
	ds_read_b32 v255, v255 offset:264
	s_waitcnt lgkmcnt(0)
	v_cmp_ne_u32_e32 vcc, 0, v255
	s_cbranch_vccz .Lxl_full_4
	v_mov_b32_e32 v0, 0
	ds_read_b32 v0, v0 offset:260

; DI unsigned xb_add(unsigned* p, unsigned v) { return __hip_atomic_fetch_add(p, v, __ATOMIC_RELAXED, __HIP_MEMORY_SCOPE_AGENT); }
; DI void xcd_barrier(const XcdBarrier& b) {
;     ...
;       __builtin_amdgcn_fence(__ATOMIC_ACQUIRE, "agent");
;       xb_add(&bar[XB_XGEN(b.x)], 1u);
;       asm volatile("s_waitcnt vmcnt(0)" ::: "memory");
.LBB0_635:
	s_or_b64 exec, exec, s[8:9]
	s_mov_b64 s[8:9], exec
	v_mbcnt_lo_u32_b32 v0, s8, 0
	v_mbcnt_hi_u32_b32 v0, s9, v0
	v_cmp_eq_u32_e32 vcc, 0, v0
	s_waitcnt vmcnt(0)
	s_cmp_lg_u32 s100, 0
	s_cbranch_scc1 .Lei_c_4
	buffer_inv sc1
.Lei_c_4:
	s_and_saveexec_b64 s[10:11], vcc
	s_cbranch_execz .LBB0_637
	s_bcnt1_i32_b64 s2, s[8:9]
	v_mov_b32_e32 v0, 0x2000
	v_mov_b32_e32 v1, s2
	global_atomic_add v0, v1, s[6:7] offset:1024

; DI unsigned xb_ld(unsigned* p) { return __hip_atomic_load(p, __ATOMIC_RELAXED, __HIP_MEMORY_SCOPE_AGENT); }
; DI unsigned xb_add(unsigned* p, unsigned v) { return __hip_atomic_fetch_add(p, v, __ATOMIC_RELAXED, __HIP_MEMORY_SCOPE_AGENT); }
; #define XB_SPIN(cond, bar) do { unsigned _sp = 0; while (cond) { __builtin_amdgcn_s_sleep(1); \
;     if ((++_sp & 255u) == 0u) { if (xb_ld(&(bar)[XB_TMO])) break; if (_sp > XB_SPIN_CAP) { atomicAdd(&(bar)[XB_TMO], 1u); break; } } } } while (0)
; DI void xcd_barrier(const XcdBarrier& b) {
;     ...
;     if (old + 1u == (gen + 1u) * nloc) {
;       __builtin_amdgcn_fence(__ATOMIC_RELEASE, "agent");
;       asm volatile("s_waitcnt vmcnt(0)" ::: "memory");
;       const unsigned og = xb_add(&bar[XB_TOP], 1u);
;       const unsigned tg = og / nx;
;       if (og + 1u == (tg + 1u) * nx) xb_add(&bar[XB_TOPGEN], 1u);
;       else XB_SPIN(xb_ld(&bar[XB_TOPGEN]) == tg, bar);
;       __builtin_amdgcn_fence(__ATOMIC_ACQUIRE, "agent");
;       xb_add(&bar[XB_XGEN(b.x)], 1u);
;       asm volatile("s_waitcnt vmcnt(0)" ::: "memory");
;     } else {
;       XB_SPIN(xb_ld(&bar[XB_XGEN(b.x)]) == gen, bar);
;       __builtin_amdgcn_fence(__ATOMIC_ACQUIRE, "agent");
;       asm volatile("s_waitcnt vmcnt(0)" ::: "memory");
;     }
.Lei_b_5:
	s_waitcnt vmcnt(0)
.LBB0_686:
	s_andn2_saveexec_b64 s[2:3], s[8:9]
	s_cbranch_execz .LBB0_706
	s_mov_b64 s[8:9], exec
	v_mov_b32_e32 v255, 0
	ds_read_b32 v255, v255 offset:264
	s_waitcnt lgkmcnt(0)
	v_cmp_ne_u32_e32 vcc, 0, v255
	s_cbranch_vccnz .LBB0_703
	buffer_wbl2 sc1
	s_waitcnt lgkmcnt(0)
	s_waitcnt vmcnt(0)
	v_mbcnt_lo_u32_b32 v0, s8, 0
	v_mbcnt_hi_u32_b32 v0, s9, v0
	v_cmp_eq_u32_e32 vcc, 0, v0
	s_and_saveexec_b64 s[10:11], vcc
	s_cbranch_execz .LBB0_689
	s_bcnt1_i32_b64 s2, s[8:9]
	v_mov_b32_e32 v2, 0xbfa3000
	v_mov_b32_e32 v3, s2
	global_atomic_add v2, v2, v3, s[86:87] offset:1024 sc0

; DI unsigned xb_ld(unsigned* p) { return __hip_atomic_load(p, __ATOMIC_RELAXED, __HIP_MEMORY_SCOPE_AGENT); }
; DI unsigned xb_add(unsigned* p, unsigned v) { return __hip_atomic_fetch_add(p, v, __ATOMIC_RELAXED, __HIP_MEMORY_SCOPE_AGENT); }
; #define XB_SPIN(cond, bar) do { unsigned _sp = 0; while (cond) { __builtin_amdgcn_s_sleep(1); \
;     if ((++_sp & 255u) == 0u) { if (xb_ld(&(bar)[XB_TMO])) break; if (_sp > XB_SPIN_CAP) { atomicAdd(&(bar)[XB_TMO], 1u); break; } } } } while (0)
; DI void xcd_barrier(const XcdBarrier& b) {
;     ...
;     if (old + 1u == (gen + 1u) * nloc) {
;       __builtin_amdgcn_fence(__ATOMIC_RELEASE, "agent");
;       asm volatile("s_waitcnt vmcnt(0)" ::: "memory");
;       const unsigned og = xb_add(&bar[XB_TOP], 1u);
;       const unsigned tg = og / nx;
;       if (og + 1u == (tg + 1u) * nx) xb_add(&bar[XB_TOPGEN], 1u);
;       else XB_SPIN(xb_ld(&bar[XB_TOPGEN]) == tg, bar);
;       __builtin_amdgcn_fence(__ATOMIC_ACQUIRE, "agent");
;       xb_add(&bar[XB_XGEN(b.x)], 1u);
;       asm volatile("s_waitcnt vmcnt(0)" ::: "memory");
;     } else {
;       XB_SPIN(xb_ld(&bar[XB_XGEN(b.x)]) == gen, bar);
;       __builtin_amdgcn_fence(__ATOMIC_ACQUIRE, "agent");
;       asm volatile("s_waitcnt vmcnt(0)" ::: "memory");
;     }
.Lei_b_6:
	s_waitcnt vmcnt(0)
.LBB0_776:
	s_andn2_saveexec_b64 s[2:3], s[8:9]
	s_cbranch_execz .LBB0_796
	s_mov_b64 s[8:9], exec
	v_mov_b32_e32 v255, 0
	ds_read_b32 v255, v255 offset:264
	s_waitcnt lgkmcnt(0)
	v_cmp_ne_u32_e32 vcc, 0, v255
	s_cbranch_vccz .Lxl_full_6
	v_mov_b32_e32 v255, 0xbfa0210
	v_mov_b32_e32 v0, 1
	global_atomic_add v255, v0, s[86:87]
	s_branch .LBB0_793

; DI unsigned xb_ld(unsigned* p) { return __hip_atomic_load(p, __ATOMIC_RELAXED, __HIP_MEMORY_SCOPE_AGENT); }
; DI unsigned xb_add(unsigned* p, unsigned v) { return __hip_atomic_fetch_add(p, v, __ATOMIC_RELAXED, __HIP_MEMORY_SCOPE_AGENT); }
; #define XB_SPIN(cond, bar) do { unsigned _sp = 0; while (cond) { __builtin_amdgcn_s_sleep(1); \
;     if ((++_sp & 255u) == 0u) { if (xb_ld(&(bar)[XB_TMO])) break; if (_sp > XB_SPIN_CAP) { atomicAdd(&(bar)[XB_TMO], 1u); break; } } } } while (0)
; DI void xcd_barrier(const XcdBarrier& b) {
;     ...
;     if (old + 1u == (gen + 1u) * nloc) {
;       __builtin_amdgcn_fence(__ATOMIC_RELEASE, "agent");
;       asm volatile("s_waitcnt vmcnt(0)" ::: "memory");
;       const unsigned og = xb_add(&bar[XB_TOP], 1u);
;       const unsigned tg = og / nx;
;       if (og + 1u == (tg + 1u) * nx) xb_add(&bar[XB_TOPGEN], 1u);
;       else XB_SPIN(xb_ld(&bar[XB_TOPGEN]) == tg, bar);
;       __builtin_amdgcn_fence(__ATOMIC_ACQUIRE, "agent");
;       xb_add(&bar[XB_XGEN(b.x)], 1u);
;       asm volatile("s_waitcnt vmcnt(0)" ::: "memory");
;     } else {
;       XB_SPIN(xb_ld(&bar[XB_XGEN(b.x)]) == gen, bar);
;       __builtin_amdgcn_fence(__ATOMIC_ACQUIRE, "agent");
;       asm volatile("s_waitcnt vmcnt(0)" ::: "memory");
;     }
.Lei_b_7:
	s_waitcnt vmcnt(0)
.LBB0_895:
	s_andn2_saveexec_b64 s[2:3], s[8:9]
	s_cbranch_execz .LBB0_915
	s_mov_b64 s[8:9], exec
	v_mov_b32_e32 v255, 0
	ds_read_b32 v255, v255 offset:264
	s_waitcnt lgkmcnt(0)
	v_cmp_ne_u32_e32 vcc, 0, v255
	s_cbranch_vccz .Lxl_full_7
	v_mov_b32_e32 v0, 0
	ds_read_b32 v0, v0 offset:260

;   DI bool next(int i, Unit& u) const {
;     const int j = rot + i * G; if (j >= ntl) return false;
;     const int mg = j / (gms * nN), rem = j - mg * (gms * nN); u.pn = rem / gms; u.pm = xcd * mper + mg * gms + (rem - u.pn * gms); return true;
.LBB0_971:
	v_readlane_b32 s2, v254, 22
	s_mul_hi_u32 s0, s2, 0x50
	s_mul_i32 s0, s0, s42
	s_sub_i32 s0, 0x50, s0
	s_sub_i32 s1, s0, s42
	s_cmp_ge_u32 s0, s42
	s_cselect_b32 s0, s1, s0
	s_sub_i32 s1, s0, s42
	s_cmp_ge_u32 s0, s42
	s_cselect_b32 s0, s1, s0
	s_sub_i32 s0, s77, s0
	s_ashr_i32 s1, s0, 31
	s_abs_i32 s0, s0
	s_mul_hi_u32 s2, s0, s2
	s_mul_i32 s2, s2, s42
	s_sub_i32 s0, s0, s2
	s_sub_i32 s2, s0, s42
	s_cmp_ge_u32 s0, s42
	s_cselect_b32 s0, s2, s0
	s_sub_i32 s2, s0, s42
	s_cmp_ge_u32 s0, s42
	s_cselect_b32 s0, s2, s0
	s_xor_b32 s0, s0, s1
	s_sub_i32 s2, s0, s1
	s_mov_b32 s100, s42
	s_movk_i32 s101, 0x60
	s_cmp_lg_u32 s42, 32
	s_cbranch_scc1 .Lp8b_keep
	s_movk_i32 s100, 16
	s_sub_i32 s2, s77, s42
	s_cmp_ge_u32 s2, 16
	s_cbranch_scc1 .Lp8b_hi
	s_add_i32 s2, s2, 64
	s_branch .Lp8b_keep
.Lp8b_hi:
	s_add_i32 s2, s2, -16
	s_movk_i32 s101, 0x40
.Lp8b_keep:
	v_mov_b32_e32 v8, v212
	s_cmp_lt_i32 s2, s101
	s_cselect_b64 s[6:7], -1, 0
	s_cmp_ge_i32 s2, s101
	v_readfirstlane_b32 s4, v8
	s_cbranch_scc1 .LBB0_973
	s_mul_hi_i32 s0, s2, 0x2aaaaaab
	s_lshr_b32 s1, s0, 31
	s_ashr_i32 s0, s0, 2
	s_add_i32 s1, s0, s1
	s_mul_i32 s0, s1, 0xffffffe8
	s_add_i32 s3, s0, s2
	s_ashr_i32 s0, s3, 31
	s_lshr_b32 s0, s0, 30
	s_add_i32 s0, s3, s0
	s_ashr_i32 s0, s0, 2
	s_lshl_b32 s5, s52, 4
	s_sub_i32 s1, s1, s0
	s_lshl_b32 s1, s1, 2
	s_add_i32 s3, s3, s5
	s_add_i32 s5, s3, s1

;   DI bool next(int i, Unit& u) const {
;     const int j = rot + i * G; if (j >= ntl) return false;
;     const int mg = j / (gms * nN), rem = j - mg * (gms * nN); u.pn = rem / gms; u.pm = xcd * mper + mg * gms + (rem - u.pn * gms); return true;
.LBB0_979:
	s_add_i32 s25, s25, 1
	s_mul_i32 s1, s25, s100
	s_add_i32 s1, s1, s2
	s_cmp_lt_i32 s1, s101
	s_cselect_b64 s[44:45], -1, 0
	s_cmp_ge_i32 s1, s101
	s_cbranch_scc1 .LBB0_981
	s_mul_hi_i32 s4, s1, 0x2aaaaaab
	s_lshr_b32 s8, s4, 31
	s_ashr_i32 s4, s4, 2
	s_add_i32 s4, s4, s8
	s_mul_i32 s8, s4, 0xffffffe8
	s_add_i32 s1, s8, s1
	s_ashr_i32 s8, s1, 31
	s_lshr_b32 s8, s8, 30
	s_add_i32 s8, s1, s8
	s_ashr_i32 s36, s8, 2
	s_sub_i32 s4, s4, s36
	s_lshl_b32 s4, s4, 2
	s_add_i32 s1, s1, s93
	s_add_i32 s4, s1, s4

; DI unsigned xb_ld(unsigned* p) { return __hip_atomic_load(p, __ATOMIC_RELAXED, __HIP_MEMORY_SCOPE_AGENT); }
; DI unsigned xb_add(unsigned* p, unsigned v) { return __hip_atomic_fetch_add(p, v, __ATOMIC_RELAXED, __HIP_MEMORY_SCOPE_AGENT); }
; #define XB_SPIN(cond, bar) do { unsigned _sp = 0; while (cond) { __builtin_amdgcn_s_sleep(1); \
;     if ((++_sp & 255u) == 0u) { if (xb_ld(&(bar)[XB_TMO])) break; if (_sp > XB_SPIN_CAP) { atomicAdd(&(bar)[XB_TMO], 1u); break; } } } } while (0)
; DI void xcd_barrier(const XcdBarrier& b) {
;     ...
;     if (old + 1u == (gen + 1u) * nloc) {
;       __builtin_amdgcn_fence(__ATOMIC_RELEASE, "agent");
;       asm volatile("s_waitcnt vmcnt(0)" ::: "memory");
;       const unsigned og = xb_add(&bar[XB_TOP], 1u);
;       const unsigned tg = og / nx;
;       if (og + 1u == (tg + 1u) * nx) xb_add(&bar[XB_TOPGEN], 1u);
;       else XB_SPIN(xb_ld(&bar[XB_TOPGEN]) == tg, bar);
;       __builtin_amdgcn_fence(__ATOMIC_ACQUIRE, "agent");
;       xb_add(&bar[XB_XGEN(b.x)], 1u);
;       asm volatile("s_waitcnt vmcnt(0)" ::: "memory");
;     } else {
;       XB_SPIN(xb_ld(&bar[XB_XGEN(b.x)]) == gen, bar);
;       __builtin_amdgcn_fence(__ATOMIC_ACQUIRE, "agent");
;       asm volatile("s_waitcnt vmcnt(0)" ::: "memory");
;     }
.Lei_b_8:
	s_waitcnt vmcnt(0)
.LBB0_1089:
	s_andn2_saveexec_b64 s[2:3], s[8:9]
	s_cbranch_execz .LBB0_1109
	s_mov_b64 s[8:9], exec
	v_mov_b32_e32 v255, 0
	ds_read_b32 v255, v255 offset:264
	s_waitcnt lgkmcnt(0)
	v_cmp_ne_u32_e32 vcc, 0, v255
	s_cbranch_vccnz .LBB0_1106
	buffer_wbl2 sc1
	s_waitcnt lgkmcnt(0)
	s_waitcnt vmcnt(0)
	v_mbcnt_lo_u32_b32 v0, s8, 0
	v_mbcnt_hi_u32_b32 v0, s9, v0
	v_cmp_eq_u32_e32 vcc, 0, v0
	s_and_saveexec_b64 s[10:11], vcc
	s_cbranch_execz .LBB0_1092
	s_bcnt1_i32_b64 s2, s[8:9]
	v_mov_b32_e32 v2, 0xbfa3000
	v_mov_b32_e32 v3, s2
	global_atomic_add v2, v2, v3, s[86:87] offset:1024 sc0

; DI unsigned xb_add(unsigned* p, unsigned v) { return __hip_atomic_fetch_add(p, v, __ATOMIC_RELAXED, __HIP_MEMORY_SCOPE_AGENT); }
; DI void xcd_barrier(const XcdBarrier& b) {
;     ...
;   if (threadIdx.x == 0) {
;     unsigned* bar = b.bar;
;     __builtin_amdgcn_s_waitcnt(0);
;     unsigned nloc = b.st[0], nx = b.st[1];
;     if (nloc == 0u) { xcd_barrier_complete(bar, b.x, nloc, nx); b.st[0] = nloc; b.st[1] = nx; }
;     const unsigned old = xb_add(&bar[XB_XSUB(b.x)], 1u);
.LBB0_1128:
	s_mov_b64 s[6:7], exec
	s_lshl_b32 s2, s78, 8
	v_mbcnt_lo_u32_b32 v0, s6, 0
	s_add_u32 s2, s92, s2
	v_mbcnt_hi_u32_b32 v0, s7, v0
	s_addc_u32 s3, s93, 0
	v_cmp_eq_u32_e32 vcc, 0, v0
	s_and_saveexec_b64 s[8:9], vcc
	s_cbranch_execz .LBB0_1130
	v_mov_b32_e32 v255, 0
	ds_read_b32 v255, v255 offset:264
	s_waitcnt lgkmcnt(0)
	v_readfirstlane_b32 s100, v255
	s_cmp_lg_u32 s100, 0
	s_cbranch_scc0 .Lei_a_9
	buffer_inv sc1
.Lei_a_9:
	s_bcnt1_i32_b64 s4, s[6:7]
	v_mov_b32_e32 v3, 0x1000
	v_mov_b32_e32 v4, s4
	global_atomic_add v3, v3, v4, s[2:3] offset:1024 sc0

; DI unsigned xb_ld(unsigned* p) { return __hip_atomic_load(p, __ATOMIC_RELAXED, __HIP_MEMORY_SCOPE_AGENT); }
; DI unsigned xb_add(unsigned* p, unsigned v) { return __hip_atomic_fetch_add(p, v, __ATOMIC_RELAXED, __HIP_MEMORY_SCOPE_AGENT); }
; #define XB_SPIN(cond, bar) do { unsigned _sp = 0; while (cond) { __builtin_amdgcn_s_sleep(1); \
;     if ((++_sp & 255u) == 0u) { if (xb_ld(&(bar)[XB_TMO])) break; if (_sp > XB_SPIN_CAP) { atomicAdd(&(bar)[XB_TMO], 1u); break; } } } } while (0)
; DI void xcd_barrier(const XcdBarrier& b) {
;     ...
;     if (old + 1u == (gen + 1u) * nloc) {
;       __builtin_amdgcn_fence(__ATOMIC_RELEASE, "agent");
;       asm volatile("s_waitcnt vmcnt(0)" ::: "memory");
;       const unsigned og = xb_add(&bar[XB_TOP], 1u);
;       const unsigned tg = og / nx;
;       if (og + 1u == (tg + 1u) * nx) xb_add(&bar[XB_TOPGEN], 1u);
;       else XB_SPIN(xb_ld(&bar[XB_TOPGEN]) == tg, bar);
;       __builtin_amdgcn_fence(__ATOMIC_ACQUIRE, "agent");
;       xb_add(&bar[XB_XGEN(b.x)], 1u);
;       asm volatile("s_waitcnt vmcnt(0)" ::: "memory");
;     } else {
;       XB_SPIN(xb_ld(&bar[XB_XGEN(b.x)]) == gen, bar);
;       __builtin_amdgcn_fence(__ATOMIC_ACQUIRE, "agent");
;       asm volatile("s_waitcnt vmcnt(0)" ::: "memory");
;     }
.Lei_b_9:
	s_waitcnt vmcnt(0)
.LBB0_1144:
	s_andn2_saveexec_b64 s[4:5], s[6:7]
	s_cbranch_execz .LBB0_1164
	s_mov_b64 s[6:7], exec
	v_mov_b32_e32 v255, 0
	ds_read_b32 v255, v255 offset:264
	s_waitcnt lgkmcnt(0)
	v_cmp_ne_u32_e32 vcc, 0, v255
	s_cbranch_vccnz .LBB0_1161
	buffer_wbl2 sc1
	s_waitcnt lgkmcnt(0)
	s_waitcnt vmcnt(0)
	v_mbcnt_lo_u32_b32 v0, s6, 0
	v_mbcnt_hi_u32_b32 v0, s7, v0
	v_cmp_eq_u32_e32 vcc, 0, v0
	s_and_saveexec_b64 s[8:9], vcc
	s_cbranch_execz .LBB0_1147
	s_bcnt1_i32_b64 s4, s[6:7]
	v_mov_b32_e32 v2, 0xbfa3000
	v_mov_b32_e32 v3, s4
	global_atomic_add v2, v2, v3, s[86:87] offset:1024 sc0

; DI unsigned xb_add(unsigned* p, unsigned v) { return __hip_atomic_fetch_add(p, v, __ATOMIC_RELAXED, __HIP_MEMORY_SCOPE_AGENT); }
; DI void xcd_barrier(const XcdBarrier& b) {
;     ...
;       __builtin_amdgcn_fence(__ATOMIC_ACQUIRE, "agent");
;       xb_add(&bar[XB_XGEN(b.x)], 1u);
;       asm volatile("s_waitcnt vmcnt(0)" ::: "memory");
.Lei_c_9:
	s_and_saveexec_b64 s[8:9], vcc
	s_cbranch_execz .LBB0_1163
	s_bcnt1_i32_b64 s4, s[6:7]
	v_mov_b32_e32 v0, 0x2000
	v_mov_b32_e32 v1, s4
	global_atomic_add v0, v1, s[2:3] offset:1024

; DI unsigned xb_ld(unsigned* p) { return __hip_atomic_load(p, __ATOMIC_RELAXED, __HIP_MEMORY_SCOPE_AGENT); }
; DI unsigned xb_add(unsigned* p, unsigned v) { return __hip_atomic_fetch_add(p, v, __ATOMIC_RELAXED, __HIP_MEMORY_SCOPE_AGENT); }
; #define XB_SPIN(cond, bar) do { unsigned _sp = 0; while (cond) { __builtin_amdgcn_s_sleep(1); \
;     if ((++_sp & 255u) == 0u) { if (xb_ld(&(bar)[XB_TMO])) break; if (_sp > XB_SPIN_CAP) { atomicAdd(&(bar)[XB_TMO], 1u); break; } } } } while (0)
; DI void xcd_barrier(const XcdBarrier& b) {
;     ...
;     if (old + 1u == (gen + 1u) * nloc) {
;       __builtin_amdgcn_fence(__ATOMIC_RELEASE, "agent");
;       asm volatile("s_waitcnt vmcnt(0)" ::: "memory");
;       const unsigned og = xb_add(&bar[XB_TOP], 1u);
;       const unsigned tg = og / nx;
;       if (og + 1u == (tg + 1u) * nx) xb_add(&bar[XB_TOPGEN], 1u);
;       else XB_SPIN(xb_ld(&bar[XB_TOPGEN]) == tg, bar);
;       __builtin_amdgcn_fence(__ATOMIC_ACQUIRE, "agent");
;       xb_add(&bar[XB_XGEN(b.x)], 1u);
;       asm volatile("s_waitcnt vmcnt(0)" ::: "memory");
;     } else {
;       XB_SPIN(xb_ld(&bar[XB_XGEN(b.x)]) == gen, bar);
;       __builtin_amdgcn_fence(__ATOMIC_ACQUIRE, "agent");
;       asm volatile("s_waitcnt vmcnt(0)" ::: "memory");
;     }
.Lei_b_10:
	s_waitcnt vmcnt(0)
.LBB0_1269:
	s_andn2_saveexec_b64 s[4:5], s[6:7]
	s_cbranch_execz .LBB0_1289
	s_mov_b64 s[6:7], exec
	v_mov_b32_e32 v255, 0
	ds_read_b32 v255, v255 offset:264
	s_waitcnt lgkmcnt(0)
	v_cmp_ne_u32_e32 vcc, 0, v255
	s_cbranch_vccz .Lxl_full_10
	v_mov_b32_e32 v255, 0xbfa020c
	v_mov_b32_e32 v0, 1
	global_atomic_add v255, v0, s[86:87]
	s_branch .LBB0_1286

; DI unsigned xb_ld(unsigned* p) { return __hip_atomic_load(p, __ATOMIC_RELAXED, __HIP_MEMORY_SCOPE_AGENT); }
; DI unsigned xb_add(unsigned* p, unsigned v) { return __hip_atomic_fetch_add(p, v, __ATOMIC_RELAXED, __HIP_MEMORY_SCOPE_AGENT); }
; #define XB_SPIN(cond, bar) do { unsigned _sp = 0; while (cond) { __builtin_amdgcn_s_sleep(1); \
;     if ((++_sp & 255u) == 0u) { if (xb_ld(&(bar)[XB_TMO])) break; if (_sp > XB_SPIN_CAP) { atomicAdd(&(bar)[XB_TMO], 1u); break; } } } } while (0)
; DI void xcd_barrier(const XcdBarrier& b) {
;     ...
;     if (old + 1u == (gen + 1u) * nloc) {
;       __builtin_amdgcn_fence(__ATOMIC_RELEASE, "agent");
;       asm volatile("s_waitcnt vmcnt(0)" ::: "memory");
;       const unsigned og = xb_add(&bar[XB_TOP], 1u);
;       const unsigned tg = og / nx;
;       if (og + 1u == (tg + 1u) * nx) xb_add(&bar[XB_TOPGEN], 1u);
;       else XB_SPIN(xb_ld(&bar[XB_TOPGEN]) == tg, bar);
;       __builtin_amdgcn_fence(__ATOMIC_ACQUIRE, "agent");
;       xb_add(&bar[XB_XGEN(b.x)], 1u);
;       asm volatile("s_waitcnt vmcnt(0)" ::: "memory");
;     } else {
;       XB_SPIN(xb_ld(&bar[XB_XGEN(b.x)]) == gen, bar);
;       __builtin_amdgcn_fence(__ATOMIC_ACQUIRE, "agent");
;       asm volatile("s_waitcnt vmcnt(0)" ::: "memory");
;     }
.Lei_b_11:
	s_waitcnt vmcnt(0)
.LBB0_1355:
	s_andn2_saveexec_b64 s[4:5], s[6:7]
	s_cbranch_execz .LBB0_1375
	s_mov_b64 s[6:7], exec
	v_mov_b32_e32 v255, 0
	ds_read_b32 v255, v255 offset:264
	s_waitcnt lgkmcnt(0)
	v_cmp_ne_u32_e32 vcc, 0, v255
	s_cbranch_vccz .Lxl_full_11
	v_mov_b32_e32 v0, 0
	ds_read_b32 v0, v0 offset:260

; DI unsigned xb_ld(unsigned* p) { return __hip_atomic_load(p, __ATOMIC_RELAXED, __HIP_MEMORY_SCOPE_AGENT); }
; DI unsigned xb_add(unsigned* p, unsigned v) { return __hip_atomic_fetch_add(p, v, __ATOMIC_RELAXED, __HIP_MEMORY_SCOPE_AGENT); }
; #define XB_SPIN(cond, bar) do { unsigned _sp = 0; while (cond) { __builtin_amdgcn_s_sleep(1); \
;     if ((++_sp & 255u) == 0u) { if (xb_ld(&(bar)[XB_TMO])) break; if (_sp > XB_SPIN_CAP) { atomicAdd(&(bar)[XB_TMO], 1u); break; } } } } while (0)
; DI void xcd_barrier(const XcdBarrier& b) {
;     ...
;     if (old + 1u == (gen + 1u) * nloc) {
;       __builtin_amdgcn_fence(__ATOMIC_RELEASE, "agent");
;       asm volatile("s_waitcnt vmcnt(0)" ::: "memory");
;       const unsigned og = xb_add(&bar[XB_TOP], 1u);
;       const unsigned tg = og / nx;
;       if (og + 1u == (tg + 1u) * nx) xb_add(&bar[XB_TOPGEN], 1u);
;       else XB_SPIN(xb_ld(&bar[XB_TOPGEN]) == tg, bar);
;       __builtin_amdgcn_fence(__ATOMIC_ACQUIRE, "agent");
;       xb_add(&bar[XB_XGEN(b.x)], 1u);
;       asm volatile("s_waitcnt vmcnt(0)" ::: "memory");
;     } else {
;       XB_SPIN(xb_ld(&bar[XB_XGEN(b.x)]) == gen, bar);
;       __builtin_amdgcn_fence(__ATOMIC_ACQUIRE, "agent");
;       asm volatile("s_waitcnt vmcnt(0)" ::: "memory");
;     }
.Lei_b_12:
	s_waitcnt vmcnt(0)
.LBB0_1423:
	s_andn2_saveexec_b64 s[4:5], s[6:7]
	s_cbranch_execz .LBB0_1443
	s_mov_b64 s[6:7], exec
	v_mov_b32_e32 v255, 0
	ds_read_b32 v255, v255 offset:264
	s_waitcnt lgkmcnt(0)
	v_cmp_ne_u32_e32 vcc, 0, v255
	s_cbranch_vccnz .LBB0_1440
	buffer_wbl2 sc1
	s_waitcnt lgkmcnt(0)
	s_waitcnt vmcnt(0)
	v_mbcnt_lo_u32_b32 v0, s6, 0
	v_mbcnt_hi_u32_b32 v0, s7, v0
	v_cmp_eq_u32_e32 vcc, 0, v0
	s_and_saveexec_b64 s[8:9], vcc
	s_cbranch_execz .LBB0_1426
	s_bcnt1_i32_b64 s4, s[6:7]
	v_mov_b32_e32 v2, 0xbfa3000
	v_mov_b32_e32 v3, s4
	global_atomic_add v2, v2, v3, s[86:87] offset:1024 sc0

; #define LAS __attribute__((address_space(3)))
; __global__ void __launch_bounds__(NTHREADS, 2) fwd_megakernel(Params p) {
;   extern __shared__ __attribute__((aligned(16))) char smem[];
;   cg::grid_group grid = cg::this_grid();
;   char* ws = p.ws;
;   int toff = 0;
;   __shared__ uint4 xb_words;
;   if (threadIdx.x == 0) xb_words = make_uint4(0u, 0u, 0u, 0u);
;   __syncthreads();
;   const XcdBarrier xb = xcd_barrier_post((unsigned*)(ws + O_BAR), (volatile LAS unsigned*)&xb_words);
	.amdhsa_kernel _Z14fwd_megakernel6Params
		.amdhsa_group_segment_fixed_size 272
		.amdhsa_private_segment_fixed_size 0
		.amdhsa_kernarg_size 432
		.amdhsa_user_sgpr_count 2
		.amdhsa_user_sgpr_dispatch_ptr 0
		.amdhsa_user_sgpr_queue_ptr 0
		.amdhsa_user_sgpr_kernarg_segment_ptr 1
		.amdhsa_user_sgpr_dispatch_id 0
		.amdhsa_user_sgpr_kernarg_preload_length 0
		.amdhsa_user_sgpr_kernarg_preload_offset 0
		.amdhsa_user_sgpr_private_segment_size 0
		.amdhsa_uses_dynamic_stack 0
		.amdhsa_enable_private_segment 0
		.amdhsa_system_sgpr_workgroup_id_x 1
		.amdhsa_system_sgpr_workgroup_id_y 0
		.amdhsa_system_sgpr_workgroup_id_z 0
		.amdhsa_system_sgpr_workgroup_info 0
		.amdhsa_system_vgpr_workitem_id 2
		.amdhsa_next_free_vgpr 256
		.amdhsa_next_free_sgpr 102
		.amdhsa_accum_offset 256
		.amdhsa_reserve_vcc 1
		.amdhsa_float_round_mode_32 0
		.amdhsa_float_round_mode_16_64 0
		.amdhsa_float_denorm_mode_32 3
		.amdhsa_float_denorm_mode_16_64 3
		.amdhsa_dx10_clamp 1
		.amdhsa_ieee_mode 1
		.amdhsa_fp16_overflow 0
		.amdhsa_tg_split 0
		.amdhsa_exception_fp_ieee_invalid_op 0
		.amdhsa_exception_fp_denorm_src 0
		.amdhsa_exception_fp_ieee_div_zero 0
		.amdhsa_exception_fp_ieee_overflow 0
		.amdhsa_exception_fp_ieee_underflow 0
		.amdhsa_exception_fp_ieee_inexact 0
		.amdhsa_exception_int_div_zero 0
	.end_amdhsa_kernel

amdhsa.kernels:
  - .agpr_count:     0
    .args:
      - .offset:         0
        .size:           176
        .value_kind:     by_value
      - .offset:         176
        .size:           4
        .value_kind:     hidden_block_count_x
      - .offset:         180
        .size:           4
        .value_kind:     hidden_block_count_y
      - .offset:         184
        .size:           4
        .value_kind:     hidden_block_count_z
      - .offset:         188
        .size:           2
        .value_kind:     hidden_group_size_x
      - .offset:         190
        .size:           2
        .value_kind:     hidden_group_size_y
      - .offset:         192
        .size:           2
        .value_kind:     hidden_group_size_z
      - .offset:         194
        .size:           2
        .value_kind:     hidden_remainder_x
      - .offset:         196
        .size:           2
        .value_kind:     hidden_remainder_y
      - .offset:         198
        .size:           2
        .value_kind:     hidden_remainder_z
      - .offset:         216
        .size:           8
        .value_kind:     hidden_global_offset_x
      - .offset:         224
        .size:           8
        .value_kind:     hidden_global_offset_y
      - .offset:         232
        .size:           8
        .value_kind:     hidden_global_offset_z
      - .offset:         240
        .size:           2
        .value_kind:     hidden_grid_dims
      - .offset:         264
        .size:           8
        .value_kind:     hidden_multigrid_sync_arg
      - .offset:         296
        .size:           4
        .value_kind:     hidden_dynamic_lds_size
    .group_segment_fixed_size: 272
    .kernarg_segment_align: 8
    .kernarg_segment_size: 432
    .language:       OpenCL C
    .language_version:
      - 2
      - 0
    .max_flat_workgroup_size: 512
    .name:           _Z14fwd_megakernel6Params
    .private_segment_fixed_size: 0
    .sgpr_count:     108
    .sgpr_spill_count: 34
    .symbol:         _Z14fwd_megakernel6Params.kd
    .uniform_work_group_size: 1
    .uses_dynamic_stack: false
    .vgpr_count:     256
    .vgpr_spill_count: 0
    .wavefront_size: 64
